# phase-B gate epilogue: bias add, -log2e scale and +1 of the sigmoid done with packed-f32 ops (bit-identical), on top of v10
# speedup vs baseline: 1.0051x; 1.0050x over previous
;     __device__ __forceinline__ void operator()(const AccT& acc, const Unit& u, int wr, int wc, int fr, int fq) const {
;         const int row0 = u.pm * 256 + wr * 64 + fr, col0 = u.pn * 256 + wc * 32 + 8 * fq;
;         if (u.aux == 0) {
;             const bool gate = u.pn >= 12;
;             float rsv[2][4]; f32x4 bb0[2], bb1[2];
; #pragma unroll
;             for (int ai = 0; ai < 2; ++ai)
; #pragma unroll
;                 for (int m = 0; m < 4; ++m) rsv[ai][m] = SS[row0 + ai * 128 + m * 16];
; #pragma unroll
;             for (int bj = 0; bj < 2; ++bj) { bb0[bj] = (f32x4){0.f, 0.f, 0.f, 0.f}; bb1[bj] = bb0[bj];
;                 if (gate) { bb0[bj] = *(const f32x4*)(bg + col0 + bj * 128 - ZG); bb1[bj] = *(const f32x4*)(bg + col0 + bj * 128 - ZG + 4); } }
.Lqk_no:
	v_mov_b32_e32 v178, 0xbfb8aa3b
	v_mov_b32_e32 v179, 0xbfb8aa3b
	v_or_b32_e32 v168, 16, v160
	v_or_b32_e32 v166, 32, v160
	v_or_b32_e32 v164, 48, v160
	v_lshl_add_u64 v[130:131], v[160:161], 2, s[76:77]
	v_ashrrev_i32_e32 v169, 31, v168
	v_ashrrev_i32_e32 v167, 31, v166
	v_ashrrev_i32_e32 v165, 31, v164
	v_lshl_add_u64 v[132:133], v[168:169], 2, s[76:77]
	v_lshl_add_u64 v[134:135], v[166:167], 2, s[76:77]
	v_lshl_add_u64 v[136:137], v[164:165], 2, s[76:77]
	global_load_dword v173, v[130:131], off
	global_load_dword v172, v[132:133], off
	global_load_dword v171, v[134:135], off
	global_load_dword v170, v[136:137], off
	global_load_dword v169, v[130:131], off offset:512
	global_load_dword v167, v[130:131], off offset:576
	global_load_dword v165, v[130:131], off offset:640
	global_load_dword v161, v[130:131], off offset:704
	s_cmp_gt_i32 s16, 11
	v_mov_b32_e32 v130, v158
	v_mov_b32_e32 v131, v0
	s_cselect_b64 s[18:19], -1, 0
	s_cmp_lt_i32 s16, 12
	v_lshl_add_u64 v[162:163], v[130:131], 2, s[66:67]
	v_mov_b32_e32 v130, 0
	v_mov_b32_e32 v138, 0
	v_mov_b32_e32 v139, 0
	v_mov_b32_e32 v140, 0
	v_mov_b32_e32 v141, 0
	v_mov_b32_e32 v142, 0
	v_mov_b32_e32 v143, 0
	v_mov_b32_e32 v144, 0
	v_mov_b32_e32 v145, 0
	s_cbranch_scc1 .LBB0_1110
	s_movk_i32 s0, 0xd000
	v_add_co_u32_e32 v134, vcc, 0xffffd000, v162
	s_mov_b32 s1, -1
	s_nop 0
	v_addc_co_u32_e32 v135, vcc, -1, v163, vcc
	v_lshl_add_u64 v[132:133], v[162:163], 0, s[0:1]
	global_load_dwordx4 v[142:145], v[134:135], off
	global_load_dwordx4 v[138:141], v[132:133], off offset:16

; __device__ __forceinline__ float rstd_of(float ss) { return rsqrtf(ss * (1.0f / DM) + EPS); }
; __device__ __forceinline__ float sigmoidf_(float x) { return __builtin_amdgcn_rcpf(1.0f + __expf(-x)); }
; __device__ __forceinline__ u32x4 pack8(const f32x4 a, const f32x4 b) { u32x4 w; w.x = cvt_pk_bf16(a[0], a[1]); w.y = cvt_pk_bf16(a[2], a[3]); w.z = cvt_pk_bf16(b[0], b[1]); w.w = cvt_pk_bf16(b[2], b[3]); return w; }
;     __device__ __forceinline__ void operator()(const AccT& acc, const Unit& u, int wr, int wc, int fr, int fq) const {
;     ...
;             for (int bj = 0; bj < 2; ++bj) {
;                 const f32x4 b0 = bb0[bj], b1 = bb1[bj];
; #pragma unroll
;                 for (int ai = 0; ai < 2; ++ai)
; #pragma unroll
;                     for (int m = 0; m < 4; ++m) {
;                         const float rs = rstd_of(rsv[ai][m]);
;                         f32x4 v0 = acc[ai][bj][m][0] * rs, v1 = acc[ai][bj][m][1] * rs;
;                         if (gate) {
; #pragma unroll
;                             for (int j = 0; j < 4; ++j) { v0[j] = sigmoidf_(v0[j] + b0[j]); v1[j] = sigmoidf_(v1[j] + b1[j]); } }
;                         *(u32x4*)(Z + (size_t)(row0 + ai * 128 + m * 16) * ZW + col0 + bj * 128) = pack8(v0, v1);
.LBB0_1112:
	s_waitcnt vmcnt(0)
	v_fmamk_f32 v162, v173, 0x3a000000, v251
	v_mul_f32_e32 v163, 0x4b800000, v162
	v_cmp_gt_f32_e32 vcc, s38, v162
	s_nop 1
	v_cndmask_b32_e32 v162, v162, v163, vcc
	v_rsq_f32_e32 v162, v162
	s_nop 0
	v_mul_f32_e32 v163, 0x45800000, v162
	v_cndmask_b32_e32 v162, v162, v163, vcc
	v_pk_mul_f32 v[128:129], v[128:129], v[162:163] op_sel_hi:[1,0]
	v_pk_mul_f32 v[126:127], v[126:127], v[162:163] op_sel_hi:[1,0]
	v_pk_mul_f32 v[124:125], v[124:125], v[162:163] op_sel_hi:[1,0]
	s_and_b64 vcc, exec, s[0:1]
	v_pk_mul_f32 v[122:123], v[122:123], v[162:163] op_sel_hi:[1,0]
	s_cbranch_vccnz .LBB0_1114
	v_pk_add_f32 v[126:127], v[126:127], v[142:143]
	v_pk_add_f32 v[122:123], v[122:123], v[138:139]
	v_pk_add_f32 v[128:129], v[128:129], v[144:145]
	v_pk_add_f32 v[124:125], v[124:125], v[140:141]
	v_pk_mul_f32 v[126:127], v[126:127], v[178:179]
	v_pk_mul_f32 v[122:123], v[122:123], v[178:179]
	v_pk_mul_f32 v[128:129], v[128:129], v[178:179]
	v_pk_mul_f32 v[124:125], v[124:125], v[178:179]
	v_exp_f32_e32 v126, v126
	v_exp_f32_e32 v122, v122
	v_exp_f32_e32 v127, v127
	v_exp_f32_e32 v123, v123
	v_exp_f32_e32 v128, v128
	v_exp_f32_e32 v124, v124
	v_exp_f32_e32 v129, v129
	v_exp_f32_e32 v125, v125
	v_pk_add_f32 v[126:127], v[126:127], 1.0 op_sel_hi:[1,0]
	v_pk_add_f32 v[122:123], v[122:123], 1.0 op_sel_hi:[1,0]
	v_pk_add_f32 v[128:129], v[128:129], 1.0 op_sel_hi:[1,0]
	v_pk_add_f32 v[124:125], v[124:125], 1.0 op_sel_hi:[1,0]
	v_rcp_f32_e32 v126, v126
	v_rcp_f32_e32 v122, v122
	v_rcp_f32_e32 v127, v127
	v_rcp_f32_e32 v123, v123
	v_rcp_f32_e32 v128, v128
	v_rcp_f32_e32 v124, v124
	v_rcp_f32_e32 v129, v129
	v_rcp_f32_e32 v125, v125
.LBB0_1114:
	v_cvt_pk_bf16_f32 v126, v126, v127
	v_cvt_pk_bf16_f32 v127, v128, v129
	v_cvt_pk_bf16_f32 v129, v124, v125
	v_fmamk_f32 v124, v172, 0x3a000000, v251
	v_cmp_gt_f32_e32 vcc, s38, v124
	v_mul_f32_e32 v125, 0x4b800000, v124
	v_cvt_pk_bf16_f32 v128, v122, v123
	v_mov_b64_e32 v[122:123], s[30:31]
	v_cndmask_b32_e32 v124, v124, v125, vcc
	v_rsq_f32_e32 v124, v124
	v_mad_i64_i32 v[122:123], s[18:19], v160, s68, v[122:123]
	v_lshl_add_u64 v[122:123], v[158:159], 1, v[122:123]
	v_mul_f32_e32 v125, 0x45800000, v124
	v_cndmask_b32_e32 v124, v124, v125, vcc
	v_pk_mul_f32 v[120:121], v[120:121], v[124:125] op_sel_hi:[1,0]
	v_pk_mul_f32 v[118:119], v[118:119], v[124:125] op_sel_hi:[1,0]
	v_pk_mul_f32 v[116:117], v[116:117], v[124:125] op_sel_hi:[1,0]
	v_pk_mul_f32 v[114:115], v[114:115], v[124:125] op_sel_hi:[1,0]
	s_and_b64 vcc, exec, s[0:1]
	global_store_dwordx4 v[122:123], v[126:129], off
	s_cbranch_vccnz .LBB0_1116
	v_pk_add_f32 v[118:119], v[118:119], v[142:143]
	v_pk_add_f32 v[114:115], v[114:115], v[138:139]
	v_pk_add_f32 v[120:121], v[120:121], v[144:145]
	v_pk_add_f32 v[116:117], v[116:117], v[140:141]
	v_pk_mul_f32 v[118:119], v[118:119], v[178:179]
	v_pk_mul_f32 v[114:115], v[114:115], v[178:179]
	v_pk_mul_f32 v[120:121], v[120:121], v[178:179]
	v_pk_mul_f32 v[116:117], v[116:117], v[178:179]
	v_exp_f32_e32 v118, v118
	v_exp_f32_e32 v114, v114
	v_exp_f32_e32 v119, v119
	v_exp_f32_e32 v115, v115
	v_exp_f32_e32 v120, v120
	v_exp_f32_e32 v116, v116
	v_exp_f32_e32 v121, v121
	v_exp_f32_e32 v117, v117
	v_pk_add_f32 v[118:119], v[118:119], 1.0 op_sel_hi:[1,0]
	v_pk_add_f32 v[114:115], v[114:115], 1.0 op_sel_hi:[1,0]
	v_pk_add_f32 v[120:121], v[120:121], 1.0 op_sel_hi:[1,0]
	v_pk_add_f32 v[116:117], v[116:117], 1.0 op_sel_hi:[1,0]
	v_rcp_f32_e32 v118, v118
	v_rcp_f32_e32 v114, v114
	v_rcp_f32_e32 v119, v119
	v_rcp_f32_e32 v115, v115
	v_rcp_f32_e32 v120, v120
	v_rcp_f32_e32 v116, v116
	v_rcp_f32_e32 v121, v121
	v_rcp_f32_e32 v117, v117
.LBB0_1116:
	v_cvt_pk_bf16_f32 v118, v118, v119
	v_cvt_pk_bf16_f32 v119, v120, v121
	v_cvt_pk_bf16_f32 v121, v116, v117
	v_fmamk_f32 v116, v171, 0x3a000000, v251
	v_cmp_gt_f32_e32 vcc, s38, v116
	v_mul_f32_e32 v117, 0x4b800000, v116
	v_cvt_pk_bf16_f32 v120, v114, v115
	v_mov_b64_e32 v[114:115], s[30:31]
	v_cndmask_b32_e32 v116, v116, v117, vcc
	v_rsq_f32_e32 v116, v116
	v_mad_i64_i32 v[114:115], s[18:19], v168, s68, v[114:115]
	v_lshl_add_u64 v[114:115], v[158:159], 1, v[114:115]
	v_mul_f32_e32 v117, 0x45800000, v116
	v_cndmask_b32_e32 v116, v116, v117, vcc
	v_pk_mul_f32 v[112:113], v[112:113], v[116:117] op_sel_hi:[1,0]
	v_pk_mul_f32 v[110:111], v[110:111], v[116:117] op_sel_hi:[1,0]
	v_pk_mul_f32 v[108:109], v[108:109], v[116:117] op_sel_hi:[1,0]
	v_pk_mul_f32 v[106:107], v[106:107], v[116:117] op_sel_hi:[1,0]
	s_and_b64 vcc, exec, s[0:1]
	global_store_dwordx4 v[114:115], v[118:121], off
	s_cbranch_vccnz .LBB0_1118
	v_pk_add_f32 v[110:111], v[110:111], v[142:143]
	v_pk_add_f32 v[106:107], v[106:107], v[138:139]
	v_pk_add_f32 v[112:113], v[112:113], v[144:145]
	v_pk_add_f32 v[108:109], v[108:109], v[140:141]
	v_pk_mul_f32 v[110:111], v[110:111], v[178:179]
	v_pk_mul_f32 v[106:107], v[106:107], v[178:179]
	v_pk_mul_f32 v[112:113], v[112:113], v[178:179]
	v_pk_mul_f32 v[108:109], v[108:109], v[178:179]
	v_exp_f32_e32 v110, v110
	v_exp_f32_e32 v106, v106
	v_exp_f32_e32 v111, v111
	v_exp_f32_e32 v107, v107
	v_exp_f32_e32 v112, v112
	v_exp_f32_e32 v108, v108
	v_exp_f32_e32 v113, v113
	v_exp_f32_e32 v109, v109
	v_pk_add_f32 v[110:111], v[110:111], 1.0 op_sel_hi:[1,0]
	v_pk_add_f32 v[106:107], v[106:107], 1.0 op_sel_hi:[1,0]
	v_pk_add_f32 v[112:113], v[112:113], 1.0 op_sel_hi:[1,0]
	v_pk_add_f32 v[108:109], v[108:109], 1.0 op_sel_hi:[1,0]
	v_rcp_f32_e32 v110, v110
	v_rcp_f32_e32 v106, v106
	v_rcp_f32_e32 v111, v111
	v_rcp_f32_e32 v107, v107
	v_rcp_f32_e32 v112, v112
	v_rcp_f32_e32 v108, v108
	v_rcp_f32_e32 v113, v113
	v_rcp_f32_e32 v109, v109
; __device__ __forceinline__ float rstd_of(float ss) { return rsqrtf(ss * (1.0f / DM) + EPS); }
; __device__ __forceinline__ float sigmoidf_(float x) { return __builtin_amdgcn_rcpf(1.0f + __expf(-x)); }
; __device__ __forceinline__ u32x4 pack8(const f32x4 a, const f32x4 b) { u32x4 w; w.x = cvt_pk_bf16(a[0], a[1]); w.y = cvt_pk_bf16(a[2], a[3]); w.z = cvt_pk_bf16(b[0], b[1]); w.w = cvt_pk_bf16(b[2], b[3]); return w; }
;     __device__ __forceinline__ void operator()(const AccT& acc, const Unit& u, int wr, int wc, int fr, int fq) const {
;     ...
;             for (int bj = 0; bj < 2; ++bj) {
;                 const f32x4 b0 = bb0[bj], b1 = bb1[bj];
; #pragma unroll
;                 for (int ai = 0; ai < 2; ++ai)
; #pragma unroll
;                     for (int m = 0; m < 4; ++m) {
;                         const float rs = rstd_of(rsv[ai][m]);
;                         f32x4 v0 = acc[ai][bj][m][0] * rs, v1 = acc[ai][bj][m][1] * rs;
;                         if (gate) {
; #pragma unroll
;                             for (int j = 0; j < 4; ++j) { v0[j] = sigmoidf_(v0[j] + b0[j]); v1[j] = sigmoidf_(v1[j] + b1[j]); } }
;                         *(u32x4*)(Z + (size_t)(row0 + ai * 128 + m * 16) * ZW + col0 + bj * 128) = pack8(v0, v1);
.LBB0_1118:
	v_cvt_pk_bf16_f32 v110, v110, v111
	v_cvt_pk_bf16_f32 v111, v112, v113
	v_cvt_pk_bf16_f32 v113, v108, v109
	v_fmamk_f32 v108, v170, 0x3a000000, v251
	v_cmp_gt_f32_e32 vcc, s38, v108
	v_mul_f32_e32 v109, 0x4b800000, v108
	v_cvt_pk_bf16_f32 v112, v106, v107
	v_mov_b64_e32 v[106:107], s[30:31]
	v_cndmask_b32_e32 v108, v108, v109, vcc
	v_rsq_f32_e32 v108, v108
	v_mad_i64_i32 v[106:107], s[18:19], v166, s68, v[106:107]
	v_lshl_add_u64 v[106:107], v[158:159], 1, v[106:107]
	v_mul_f32_e32 v109, 0x45800000, v108
	v_cndmask_b32_e32 v108, v108, v109, vcc
	v_pk_mul_f32 v[104:105], v[104:105], v[108:109] op_sel_hi:[1,0]
	v_pk_mul_f32 v[102:103], v[102:103], v[108:109] op_sel_hi:[1,0]
	v_pk_mul_f32 v[100:101], v[100:101], v[108:109] op_sel_hi:[1,0]
	v_pk_mul_f32 v[98:99], v[98:99], v[108:109] op_sel_hi:[1,0]
	s_and_b64 vcc, exec, s[0:1]
	global_store_dwordx4 v[106:107], v[110:113], off
	s_cbranch_vccnz .LBB0_1120
	v_pk_add_f32 v[102:103], v[102:103], v[142:143]
	v_pk_add_f32 v[98:99], v[98:99], v[138:139]
	v_pk_add_f32 v[104:105], v[104:105], v[144:145]
	v_pk_add_f32 v[100:101], v[100:101], v[140:141]
	v_pk_mul_f32 v[102:103], v[102:103], v[178:179]
	v_pk_mul_f32 v[98:99], v[98:99], v[178:179]
	v_pk_mul_f32 v[104:105], v[104:105], v[178:179]
	v_pk_mul_f32 v[100:101], v[100:101], v[178:179]
	v_exp_f32_e32 v102, v102
	v_exp_f32_e32 v98, v98
	v_exp_f32_e32 v103, v103
	v_exp_f32_e32 v99, v99
	v_exp_f32_e32 v104, v104
	v_exp_f32_e32 v100, v100
	v_exp_f32_e32 v105, v105
	v_exp_f32_e32 v101, v101
	v_pk_add_f32 v[102:103], v[102:103], 1.0 op_sel_hi:[1,0]
	v_pk_add_f32 v[98:99], v[98:99], 1.0 op_sel_hi:[1,0]
	v_pk_add_f32 v[104:105], v[104:105], 1.0 op_sel_hi:[1,0]
	v_pk_add_f32 v[100:101], v[100:101], 1.0 op_sel_hi:[1,0]
	v_rcp_f32_e32 v102, v102
	v_rcp_f32_e32 v98, v98
	v_rcp_f32_e32 v103, v103
	v_rcp_f32_e32 v99, v99
	v_rcp_f32_e32 v104, v104
	v_rcp_f32_e32 v100, v100
	v_rcp_f32_e32 v105, v105
	v_rcp_f32_e32 v101, v101
.LBB0_1120:
	v_cvt_pk_bf16_f32 v102, v102, v103
	v_cvt_pk_bf16_f32 v103, v104, v105
	v_cvt_pk_bf16_f32 v105, v100, v101
	v_fmamk_f32 v100, v169, 0x3a000000, v251
	v_cmp_gt_f32_e32 vcc, s38, v100
	v_mul_f32_e32 v101, 0x4b800000, v100
	v_cvt_pk_bf16_f32 v104, v98, v99
	v_mov_b64_e32 v[98:99], s[30:31]
	v_cndmask_b32_e32 v100, v100, v101, vcc
	v_rsq_f32_e32 v100, v100
	v_mad_i64_i32 v[98:99], s[18:19], v164, s68, v[98:99]
	v_lshl_add_u64 v[98:99], v[158:159], 1, v[98:99]
	v_mul_f32_e32 v101, 0x45800000, v100
	v_cndmask_b32_e32 v100, v100, v101, vcc
	v_pk_mul_f32 v[96:97], v[96:97], v[100:101] op_sel_hi:[1,0]
	v_pk_mul_f32 v[94:95], v[94:95], v[100:101] op_sel_hi:[1,0]
	v_pk_mul_f32 v[92:93], v[92:93], v[100:101] op_sel_hi:[1,0]
	v_pk_mul_f32 v[90:91], v[90:91], v[100:101] op_sel_hi:[1,0]
	s_and_b64 vcc, exec, s[0:1]
	global_store_dwordx4 v[98:99], v[102:105], off
	s_cbranch_vccnz .LBB0_1122
	v_pk_add_f32 v[94:95], v[94:95], v[142:143]
	v_pk_add_f32 v[90:91], v[90:91], v[138:139]
	v_pk_add_f32 v[96:97], v[96:97], v[144:145]
	v_pk_add_f32 v[92:93], v[92:93], v[140:141]
	v_pk_mul_f32 v[94:95], v[94:95], v[178:179]
	v_pk_mul_f32 v[90:91], v[90:91], v[178:179]
	v_pk_mul_f32 v[96:97], v[96:97], v[178:179]
	v_pk_mul_f32 v[92:93], v[92:93], v[178:179]
	v_exp_f32_e32 v94, v94
	v_exp_f32_e32 v90, v90
	v_exp_f32_e32 v95, v95
	v_exp_f32_e32 v91, v91
	v_exp_f32_e32 v96, v96
	v_exp_f32_e32 v92, v92
	v_exp_f32_e32 v97, v97
	v_exp_f32_e32 v93, v93
	v_pk_add_f32 v[94:95], v[94:95], 1.0 op_sel_hi:[1,0]
	v_pk_add_f32 v[90:91], v[90:91], 1.0 op_sel_hi:[1,0]
	v_pk_add_f32 v[96:97], v[96:97], 1.0 op_sel_hi:[1,0]
	v_pk_add_f32 v[92:93], v[92:93], 1.0 op_sel_hi:[1,0]
	v_rcp_f32_e32 v94, v94
	v_rcp_f32_e32 v90, v90
	v_rcp_f32_e32 v95, v95
	v_rcp_f32_e32 v91, v91
	v_rcp_f32_e32 v96, v96
	v_rcp_f32_e32 v92, v92
	v_rcp_f32_e32 v97, v97
	v_rcp_f32_e32 v93, v93
.LBB0_1122:
	v_cvt_pk_bf16_f32 v94, v94, v95
	v_cvt_pk_bf16_f32 v95, v96, v97
	v_cvt_pk_bf16_f32 v97, v92, v93
	v_fmamk_f32 v92, v167, 0x3a000000, v251
	v_cmp_gt_f32_e32 vcc, s38, v92
	v_mul_f32_e32 v93, 0x4b800000, v92
	v_add_u32_e32 v101, 0x80, v160
	v_cndmask_b32_e32 v92, v92, v93, vcc
	v_rsq_f32_e32 v92, v92
	v_cvt_pk_bf16_f32 v96, v90, v91
	v_mov_b64_e32 v[90:91], s[30:31]
	v_mad_i64_i32 v[90:91], s[18:19], v101, s68, v[90:91]
	v_mul_f32_e32 v93, 0x45800000, v92
	v_cndmask_b32_e32 v92, v92, v93, vcc
	v_lshl_add_u64 v[90:91], v[158:159], 1, v[90:91]
	v_pk_mul_f32 v[88:89], v[88:89], v[92:93] op_sel_hi:[1,0]
	v_pk_mul_f32 v[86:87], v[86:87], v[92:93] op_sel_hi:[1,0]
	v_pk_mul_f32 v[84:85], v[84:85], v[92:93] op_sel_hi:[1,0]
	v_pk_mul_f32 v[82:83], v[82:83], v[92:93] op_sel_hi:[1,0]
	s_and_b64 vcc, exec, s[0:1]
	global_store_dwordx4 v[90:91], v[94:97], off
	s_cbranch_vccnz .LBB0_1124
	v_pk_add_f32 v[86:87], v[86:87], v[142:143]
	v_pk_add_f32 v[82:83], v[82:83], v[138:139]
	v_pk_add_f32 v[88:89], v[88:89], v[144:145]
	v_pk_add_f32 v[84:85], v[84:85], v[140:141]
	v_pk_mul_f32 v[86:87], v[86:87], v[178:179]
	v_pk_mul_f32 v[82:83], v[82:83], v[178:179]
	v_pk_mul_f32 v[88:89], v[88:89], v[178:179]
	v_pk_mul_f32 v[84:85], v[84:85], v[178:179]
	v_exp_f32_e32 v86, v86
	v_exp_f32_e32 v82, v82
	v_exp_f32_e32 v87, v87
	v_exp_f32_e32 v83, v83
	v_exp_f32_e32 v88, v88
	v_exp_f32_e32 v84, v84
	v_exp_f32_e32 v89, v89
	v_exp_f32_e32 v85, v85
	v_pk_add_f32 v[86:87], v[86:87], 1.0 op_sel_hi:[1,0]
	v_pk_add_f32 v[82:83], v[82:83], 1.0 op_sel_hi:[1,0]
	v_pk_add_f32 v[88:89], v[88:89], 1.0 op_sel_hi:[1,0]
	v_pk_add_f32 v[84:85], v[84:85], 1.0 op_sel_hi:[1,0]
	v_rcp_f32_e32 v86, v86
	v_rcp_f32_e32 v82, v82
	v_rcp_f32_e32 v87, v87
	v_rcp_f32_e32 v83, v83
	v_rcp_f32_e32 v88, v88
	v_rcp_f32_e32 v84, v84
	v_rcp_f32_e32 v89, v89
	v_rcp_f32_e32 v85, v85
; __device__ __forceinline__ float rstd_of(float ss) { return rsqrtf(ss * (1.0f / DM) + EPS); }
; __device__ __forceinline__ float sigmoidf_(float x) { return __builtin_amdgcn_rcpf(1.0f + __expf(-x)); }
; __device__ __forceinline__ u32x4 pack8(const f32x4 a, const f32x4 b) { u32x4 w; w.x = cvt_pk_bf16(a[0], a[1]); w.y = cvt_pk_bf16(a[2], a[3]); w.z = cvt_pk_bf16(b[0], b[1]); w.w = cvt_pk_bf16(b[2], b[3]); return w; }
;     __device__ __forceinline__ void operator()(const AccT& acc, const Unit& u, int wr, int wc, int fr, int fq) const {
;     ...
;             for (int bj = 0; bj < 2; ++bj) {
;                 const f32x4 b0 = bb0[bj], b1 = bb1[bj];
; #pragma unroll
;                 for (int ai = 0; ai < 2; ++ai)
; #pragma unroll
;                     for (int m = 0; m < 4; ++m) {
;                         const float rs = rstd_of(rsv[ai][m]);
;                         f32x4 v0 = acc[ai][bj][m][0] * rs, v1 = acc[ai][bj][m][1] * rs;
;                         if (gate) {
; #pragma unroll
;                             for (int j = 0; j < 4; ++j) { v0[j] = sigmoidf_(v0[j] + b0[j]); v1[j] = sigmoidf_(v1[j] + b1[j]); } }
;                         *(u32x4*)(Z + (size_t)(row0 + ai * 128 + m * 16) * ZW + col0 + bj * 128) = pack8(v0, v1);
.LBB0_1124:
	v_cvt_pk_bf16_f32 v86, v86, v87
	v_cvt_pk_bf16_f32 v87, v88, v89
	v_cvt_pk_bf16_f32 v89, v84, v85
	v_fmamk_f32 v84, v165, 0x3a000000, v251
	v_cmp_gt_f32_e32 vcc, s38, v84
	v_mul_f32_e32 v85, 0x4b800000, v84
	v_add_u32_e32 v93, 0x90, v160
	v_cndmask_b32_e32 v84, v84, v85, vcc
	v_rsq_f32_e32 v84, v84
	v_cvt_pk_bf16_f32 v88, v82, v83
	v_mov_b64_e32 v[82:83], s[30:31]
	v_mad_i64_i32 v[82:83], s[18:19], v93, s68, v[82:83]
	v_mul_f32_e32 v85, 0x45800000, v84
	v_cndmask_b32_e32 v84, v84, v85, vcc
	v_lshl_add_u64 v[82:83], v[158:159], 1, v[82:83]
	v_pk_mul_f32 v[80:81], v[80:81], v[84:85] op_sel_hi:[1,0]
	v_pk_mul_f32 v[78:79], v[78:79], v[84:85] op_sel_hi:[1,0]
	v_pk_mul_f32 v[76:77], v[76:77], v[84:85] op_sel_hi:[1,0]
	v_pk_mul_f32 v[74:75], v[74:75], v[84:85] op_sel_hi:[1,0]
	s_and_b64 vcc, exec, s[0:1]
	global_store_dwordx4 v[82:83], v[86:89], off
	s_cbranch_vccnz .LBB0_1126
	v_pk_add_f32 v[78:79], v[78:79], v[142:143]
	v_pk_add_f32 v[74:75], v[74:75], v[138:139]
	v_pk_add_f32 v[80:81], v[80:81], v[144:145]
	v_pk_add_f32 v[76:77], v[76:77], v[140:141]
	v_pk_mul_f32 v[78:79], v[78:79], v[178:179]
	v_pk_mul_f32 v[74:75], v[74:75], v[178:179]
	v_pk_mul_f32 v[80:81], v[80:81], v[178:179]
	v_pk_mul_f32 v[76:77], v[76:77], v[178:179]
	v_exp_f32_e32 v78, v78
	v_exp_f32_e32 v74, v74
	v_exp_f32_e32 v79, v79
	v_exp_f32_e32 v75, v75
	v_exp_f32_e32 v80, v80
	v_exp_f32_e32 v76, v76
	v_exp_f32_e32 v81, v81
	v_exp_f32_e32 v77, v77
	v_pk_add_f32 v[78:79], v[78:79], 1.0 op_sel_hi:[1,0]
	v_pk_add_f32 v[74:75], v[74:75], 1.0 op_sel_hi:[1,0]
	v_pk_add_f32 v[80:81], v[80:81], 1.0 op_sel_hi:[1,0]
	v_pk_add_f32 v[76:77], v[76:77], 1.0 op_sel_hi:[1,0]
	v_rcp_f32_e32 v78, v78
	v_rcp_f32_e32 v74, v74
	v_rcp_f32_e32 v79, v79
	v_rcp_f32_e32 v75, v75
	v_rcp_f32_e32 v80, v80
	v_rcp_f32_e32 v76, v76
	v_rcp_f32_e32 v81, v81
	v_rcp_f32_e32 v77, v77
.LBB0_1126:
	v_cvt_pk_bf16_f32 v78, v78, v79
	v_cvt_pk_bf16_f32 v79, v80, v81
	v_cvt_pk_bf16_f32 v81, v76, v77
	v_fmamk_f32 v76, v161, 0x3a000000, v251
	v_cmp_gt_f32_e32 vcc, s38, v76
	v_mul_f32_e32 v77, 0x4b800000, v76
	v_add_u32_e32 v85, 0xa0, v160
	v_cndmask_b32_e32 v76, v76, v77, vcc
	v_rsq_f32_e32 v76, v76
	v_cvt_pk_bf16_f32 v80, v74, v75
	v_mov_b64_e32 v[74:75], s[30:31]
	v_mad_i64_i32 v[74:75], s[18:19], v85, s68, v[74:75]
	v_mul_f32_e32 v77, 0x45800000, v76
	v_cndmask_b32_e32 v76, v76, v77, vcc
	v_lshl_add_u64 v[74:75], v[158:159], 1, v[74:75]
	v_pk_mul_f32 v[72:73], v[72:73], v[76:77] op_sel_hi:[1,0]
	v_pk_mul_f32 v[70:71], v[70:71], v[76:77] op_sel_hi:[1,0]
	v_pk_mul_f32 v[68:69], v[68:69], v[76:77] op_sel_hi:[1,0]
	v_pk_mul_f32 v[66:67], v[66:67], v[76:77] op_sel_hi:[1,0]
	s_and_b64 vcc, exec, s[0:1]
	global_store_dwordx4 v[74:75], v[78:81], off
	s_cbranch_vccnz .LBB0_1128
	v_pk_add_f32 v[70:71], v[70:71], v[142:143]
	v_pk_add_f32 v[66:67], v[66:67], v[138:139]
	v_pk_add_f32 v[72:73], v[72:73], v[144:145]
	v_pk_add_f32 v[68:69], v[68:69], v[140:141]
	v_pk_mul_f32 v[70:71], v[70:71], v[178:179]
	v_pk_mul_f32 v[66:67], v[66:67], v[178:179]
	v_pk_mul_f32 v[72:73], v[72:73], v[178:179]
	v_pk_mul_f32 v[68:69], v[68:69], v[178:179]
	v_exp_f32_e32 v70, v70
	v_exp_f32_e32 v66, v66
	v_exp_f32_e32 v71, v71
	v_exp_f32_e32 v67, v67
	v_exp_f32_e32 v72, v72
	v_exp_f32_e32 v68, v68
	v_exp_f32_e32 v73, v73
	v_exp_f32_e32 v69, v69
	v_pk_add_f32 v[70:71], v[70:71], 1.0 op_sel_hi:[1,0]
	v_pk_add_f32 v[66:67], v[66:67], 1.0 op_sel_hi:[1,0]
	v_pk_add_f32 v[72:73], v[72:73], 1.0 op_sel_hi:[1,0]
	v_pk_add_f32 v[68:69], v[68:69], 1.0 op_sel_hi:[1,0]
	v_rcp_f32_e32 v70, v70
	v_rcp_f32_e32 v66, v66
	v_rcp_f32_e32 v71, v71
	v_rcp_f32_e32 v67, v67
	v_rcp_f32_e32 v72, v72
	v_rcp_f32_e32 v68, v68
	v_rcp_f32_e32 v73, v73
	v_rcp_f32_e32 v69, v69
.LBB0_1128:
	v_add_u32_e32 v77, 0xb0, v160
	v_cvt_pk_bf16_f32 v70, v70, v71
	v_cvt_pk_bf16_f32 v71, v72, v73
	v_cvt_pk_bf16_f32 v72, v66, v67
	v_mov_b64_e32 v[66:67], s[30:31]
	v_mov_b32_e32 v163, v162
	v_cvt_pk_bf16_f32 v73, v68, v69
	v_mad_i64_i32 v[66:67], s[18:19], v77, s68, v[66:67]
	v_mov_b32_e32 v68, v162
	v_mov_b32_e32 v69, v162
	v_lshl_add_u64 v[66:67], v[158:159], 1, v[66:67]
	v_pk_mul_f32 v[64:65], v[64:65], v[68:69]
	v_pk_mul_f32 v[62:63], v[62:63], v[162:163]
	v_pk_mul_f32 v[60:61], v[60:61], v[68:69]
	s_and_b64 vcc, exec, s[0:1]
	v_pk_mul_f32 v[58:59], v[58:59], v[162:163]
	global_store_dwordx4 v[66:67], v[70:73], off
	s_cbranch_vccnz .LBB0_1130
	v_pk_add_f32 v[62:63], v[62:63], v[134:135]
	v_pk_add_f32 v[58:59], v[58:59], v[130:131]
	v_pk_add_f32 v[64:65], v[64:65], v[136:137]
	v_pk_add_f32 v[60:61], v[60:61], v[132:133]
	v_pk_mul_f32 v[62:63], v[62:63], v[178:179]
	v_pk_mul_f32 v[58:59], v[58:59], v[178:179]
	v_pk_mul_f32 v[64:65], v[64:65], v[178:179]
	v_pk_mul_f32 v[60:61], v[60:61], v[178:179]
	v_exp_f32_e32 v62, v62
	v_exp_f32_e32 v58, v58
	v_exp_f32_e32 v63, v63
	v_exp_f32_e32 v59, v59
	v_exp_f32_e32 v64, v64
	v_exp_f32_e32 v60, v60
	v_exp_f32_e32 v65, v65
	v_exp_f32_e32 v61, v61
	v_pk_add_f32 v[62:63], v[62:63], 1.0 op_sel_hi:[1,0]
	v_pk_add_f32 v[58:59], v[58:59], 1.0 op_sel_hi:[1,0]
	v_pk_add_f32 v[64:65], v[64:65], 1.0 op_sel_hi:[1,0]
	v_pk_add_f32 v[60:61], v[60:61], 1.0 op_sel_hi:[1,0]
	v_rcp_f32_e32 v62, v62
	v_rcp_f32_e32 v58, v58
	v_rcp_f32_e32 v63, v63
	v_rcp_f32_e32 v59, v59
	v_rcp_f32_e32 v64, v64
	v_rcp_f32_e32 v60, v60
	v_rcp_f32_e32 v65, v65
	v_rcp_f32_e32 v61, v61
; __device__ __forceinline__ float rstd_of(float ss) { return rsqrtf(ss * (1.0f / DM) + EPS); }
; __device__ __forceinline__ float sigmoidf_(float x) { return __builtin_amdgcn_rcpf(1.0f + __expf(-x)); }
; __device__ __forceinline__ u32x4 pack8(const f32x4 a, const f32x4 b) { u32x4 w; w.x = cvt_pk_bf16(a[0], a[1]); w.y = cvt_pk_bf16(a[2], a[3]); w.z = cvt_pk_bf16(b[0], b[1]); w.w = cvt_pk_bf16(b[2], b[3]); return w; }
;     __device__ __forceinline__ void operator()(const AccT& acc, const Unit& u, int wr, int wc, int fr, int fq) const {
;     ...
;             for (int bj = 0; bj < 2; ++bj) {
;                 const f32x4 b0 = bb0[bj], b1 = bb1[bj];
; #pragma unroll
;                 for (int ai = 0; ai < 2; ++ai)
; #pragma unroll
;                     for (int m = 0; m < 4; ++m) {
;                         const float rs = rstd_of(rsv[ai][m]);
;                         f32x4 v0 = acc[ai][bj][m][0] * rs, v1 = acc[ai][bj][m][1] * rs;
;                         if (gate) {
; #pragma unroll
;                             for (int j = 0; j < 4; ++j) { v0[j] = sigmoidf_(v0[j] + b0[j]); v1[j] = sigmoidf_(v1[j] + b1[j]); } }
;                         *(u32x4*)(Z + (size_t)(row0 + ai * 128 + m * 16) * ZW + col0 + bj * 128) = pack8(v0, v1);
.LBB0_1130:
	v_mov_b32_e32 v125, v124
	v_cvt_pk_bf16_f32 v62, v62, v63
	v_cvt_pk_bf16_f32 v63, v64, v65
	v_cvt_pk_bf16_f32 v64, v58, v59
	v_mov_b32_e32 v58, v124
	v_mov_b32_e32 v59, v124
	v_pk_mul_f32 v[56:57], v[56:57], v[58:59]
	v_pk_mul_f32 v[54:55], v[54:55], v[124:125]
	v_pk_mul_f32 v[52:53], v[52:53], v[58:59]
	s_and_b64 vcc, exec, s[0:1]
	v_pk_mul_f32 v[50:51], v[50:51], v[124:125]
	v_cvt_pk_bf16_f32 v65, v60, v61
	global_store_dwordx4 v[122:123], v[62:65], off offset:256
	s_cbranch_vccnz .LBB0_1132
	v_pk_add_f32 v[54:55], v[54:55], v[134:135]
	v_pk_add_f32 v[50:51], v[50:51], v[130:131]
	v_pk_add_f32 v[56:57], v[56:57], v[136:137]
	v_pk_add_f32 v[52:53], v[52:53], v[132:133]
	v_pk_mul_f32 v[54:55], v[54:55], v[178:179]
	v_pk_mul_f32 v[50:51], v[50:51], v[178:179]
	v_pk_mul_f32 v[56:57], v[56:57], v[178:179]
	v_pk_mul_f32 v[52:53], v[52:53], v[178:179]
	v_exp_f32_e32 v54, v54
	v_exp_f32_e32 v50, v50
	v_exp_f32_e32 v55, v55
	v_exp_f32_e32 v51, v51
	v_exp_f32_e32 v56, v56
	v_exp_f32_e32 v52, v52
	v_exp_f32_e32 v57, v57
	v_exp_f32_e32 v53, v53
	v_pk_add_f32 v[54:55], v[54:55], 1.0 op_sel_hi:[1,0]
	v_pk_add_f32 v[50:51], v[50:51], 1.0 op_sel_hi:[1,0]
	v_pk_add_f32 v[56:57], v[56:57], 1.0 op_sel_hi:[1,0]
	v_pk_add_f32 v[52:53], v[52:53], 1.0 op_sel_hi:[1,0]
	v_rcp_f32_e32 v54, v54
	v_rcp_f32_e32 v50, v50
	v_rcp_f32_e32 v55, v55
	v_rcp_f32_e32 v51, v51
	v_rcp_f32_e32 v56, v56
	v_rcp_f32_e32 v52, v52
	v_rcp_f32_e32 v57, v57
	v_rcp_f32_e32 v53, v53
.LBB0_1132:
	v_mov_b32_e32 v117, v116
	v_cvt_pk_bf16_f32 v54, v54, v55
	v_cvt_pk_bf16_f32 v55, v56, v57
	v_cvt_pk_bf16_f32 v56, v50, v51
	v_mov_b32_e32 v50, v116
	v_mov_b32_e32 v51, v116
	v_pk_mul_f32 v[48:49], v[48:49], v[50:51]
	v_pk_mul_f32 v[46:47], v[46:47], v[116:117]
	v_pk_mul_f32 v[44:45], v[44:45], v[50:51]
	s_and_b64 vcc, exec, s[0:1]
	v_pk_mul_f32 v[42:43], v[42:43], v[116:117]
	v_cvt_pk_bf16_f32 v57, v52, v53
	global_store_dwordx4 v[114:115], v[54:57], off offset:256
	s_cbranch_vccnz .LBB0_1134
	v_pk_add_f32 v[46:47], v[46:47], v[134:135]
	v_pk_add_f32 v[42:43], v[42:43], v[130:131]
	v_pk_add_f32 v[48:49], v[48:49], v[136:137]
	v_pk_add_f32 v[44:45], v[44:45], v[132:133]
	v_pk_mul_f32 v[46:47], v[46:47], v[178:179]
	v_pk_mul_f32 v[42:43], v[42:43], v[178:179]
	v_pk_mul_f32 v[48:49], v[48:49], v[178:179]
	v_pk_mul_f32 v[44:45], v[44:45], v[178:179]
	v_exp_f32_e32 v46, v46
	v_exp_f32_e32 v42, v42
	v_exp_f32_e32 v47, v47
	v_exp_f32_e32 v43, v43
	v_exp_f32_e32 v48, v48
	v_exp_f32_e32 v44, v44
	v_exp_f32_e32 v49, v49
	v_exp_f32_e32 v45, v45
	v_pk_add_f32 v[46:47], v[46:47], 1.0 op_sel_hi:[1,0]
	v_pk_add_f32 v[42:43], v[42:43], 1.0 op_sel_hi:[1,0]
	v_pk_add_f32 v[48:49], v[48:49], 1.0 op_sel_hi:[1,0]
	v_pk_add_f32 v[44:45], v[44:45], 1.0 op_sel_hi:[1,0]
	v_rcp_f32_e32 v46, v46
	v_rcp_f32_e32 v42, v42
	v_rcp_f32_e32 v47, v47
	v_rcp_f32_e32 v43, v43
	v_rcp_f32_e32 v48, v48
	v_rcp_f32_e32 v44, v44
	v_rcp_f32_e32 v49, v49
	v_rcp_f32_e32 v45, v45
.LBB0_1134:
	v_mov_b32_e32 v109, v108
	v_cvt_pk_bf16_f32 v46, v46, v47
	v_cvt_pk_bf16_f32 v47, v48, v49
	v_cvt_pk_bf16_f32 v48, v42, v43
	v_mov_b32_e32 v42, v108
	v_mov_b32_e32 v43, v108
	v_pk_mul_f32 v[40:41], v[40:41], v[42:43]
	v_pk_mul_f32 v[38:39], v[38:39], v[108:109]
	v_pk_mul_f32 v[36:37], v[36:37], v[42:43]
	s_and_b64 vcc, exec, s[0:1]
	v_pk_mul_f32 v[34:35], v[34:35], v[108:109]
	v_cvt_pk_bf16_f32 v49, v44, v45
	global_store_dwordx4 v[106:107], v[46:49], off offset:256
	s_cbranch_vccnz .LBB0_1136
	v_pk_add_f32 v[38:39], v[38:39], v[134:135]
	v_pk_add_f32 v[34:35], v[34:35], v[130:131]
	v_pk_add_f32 v[40:41], v[40:41], v[136:137]
	v_pk_add_f32 v[36:37], v[36:37], v[132:133]
	v_pk_mul_f32 v[38:39], v[38:39], v[178:179]
	v_pk_mul_f32 v[34:35], v[34:35], v[178:179]
	v_pk_mul_f32 v[40:41], v[40:41], v[178:179]
	v_pk_mul_f32 v[36:37], v[36:37], v[178:179]
	v_exp_f32_e32 v38, v38
	v_exp_f32_e32 v34, v34
	v_exp_f32_e32 v39, v39
	v_exp_f32_e32 v35, v35
	v_exp_f32_e32 v40, v40
	v_exp_f32_e32 v36, v36
	v_exp_f32_e32 v41, v41
	v_exp_f32_e32 v37, v37
	v_pk_add_f32 v[38:39], v[38:39], 1.0 op_sel_hi:[1,0]
	v_pk_add_f32 v[34:35], v[34:35], 1.0 op_sel_hi:[1,0]
	v_pk_add_f32 v[40:41], v[40:41], 1.0 op_sel_hi:[1,0]
	v_pk_add_f32 v[36:37], v[36:37], 1.0 op_sel_hi:[1,0]
	v_rcp_f32_e32 v38, v38
	v_rcp_f32_e32 v34, v34
	v_rcp_f32_e32 v39, v39
	v_rcp_f32_e32 v35, v35
	v_rcp_f32_e32 v40, v40
	v_rcp_f32_e32 v36, v36
	v_rcp_f32_e32 v41, v41
	v_rcp_f32_e32 v37, v37
; __device__ __forceinline__ float rstd_of(float ss) { return rsqrtf(ss * (1.0f / DM) + EPS); }
; __device__ __forceinline__ float sigmoidf_(float x) { return __builtin_amdgcn_rcpf(1.0f + __expf(-x)); }
; __device__ __forceinline__ u32x4 pack8(const f32x4 a, const f32x4 b) { u32x4 w; w.x = cvt_pk_bf16(a[0], a[1]); w.y = cvt_pk_bf16(a[2], a[3]); w.z = cvt_pk_bf16(b[0], b[1]); w.w = cvt_pk_bf16(b[2], b[3]); return w; }
;     __device__ __forceinline__ void operator()(const AccT& acc, const Unit& u, int wr, int wc, int fr, int fq) const {
;     ...
;             for (int bj = 0; bj < 2; ++bj) {
;                 const f32x4 b0 = bb0[bj], b1 = bb1[bj];
; #pragma unroll
;                 for (int ai = 0; ai < 2; ++ai)
; #pragma unroll
;                     for (int m = 0; m < 4; ++m) {
;                         const float rs = rstd_of(rsv[ai][m]);
;                         f32x4 v0 = acc[ai][bj][m][0] * rs, v1 = acc[ai][bj][m][1] * rs;
;                         if (gate) {
; #pragma unroll
;                             for (int j = 0; j < 4; ++j) { v0[j] = sigmoidf_(v0[j] + b0[j]); v1[j] = sigmoidf_(v1[j] + b1[j]); } }
;                         *(u32x4*)(Z + (size_t)(row0 + ai * 128 + m * 16) * ZW + col0 + bj * 128) = pack8(v0, v1);
.LBB0_1136:
	v_mov_b32_e32 v101, v100
	v_cvt_pk_bf16_f32 v38, v38, v39
	v_cvt_pk_bf16_f32 v39, v40, v41
	v_cvt_pk_bf16_f32 v40, v34, v35
	v_mov_b32_e32 v34, v100
	v_mov_b32_e32 v35, v100
	v_pk_mul_f32 v[32:33], v[32:33], v[34:35]
	v_pk_mul_f32 v[30:31], v[30:31], v[100:101]
	v_pk_mul_f32 v[28:29], v[28:29], v[34:35]
	s_and_b64 vcc, exec, s[0:1]
	v_pk_mul_f32 v[26:27], v[26:27], v[100:101]
	v_cvt_pk_bf16_f32 v41, v36, v37
	global_store_dwordx4 v[98:99], v[38:41], off offset:256
	s_cbranch_vccnz .LBB0_1138
	v_pk_add_f32 v[30:31], v[30:31], v[134:135]
	v_pk_add_f32 v[26:27], v[26:27], v[130:131]
	v_pk_add_f32 v[32:33], v[32:33], v[136:137]
	v_pk_add_f32 v[28:29], v[28:29], v[132:133]
	v_pk_mul_f32 v[30:31], v[30:31], v[178:179]
	v_pk_mul_f32 v[26:27], v[26:27], v[178:179]
	v_pk_mul_f32 v[32:33], v[32:33], v[178:179]
	v_pk_mul_f32 v[28:29], v[28:29], v[178:179]
	v_exp_f32_e32 v30, v30
	v_exp_f32_e32 v26, v26
	v_exp_f32_e32 v31, v31
	v_exp_f32_e32 v27, v27
	v_exp_f32_e32 v32, v32
	v_exp_f32_e32 v28, v28
	v_exp_f32_e32 v33, v33
	v_exp_f32_e32 v29, v29
	v_pk_add_f32 v[30:31], v[30:31], 1.0 op_sel_hi:[1,0]
	v_pk_add_f32 v[26:27], v[26:27], 1.0 op_sel_hi:[1,0]
	v_pk_add_f32 v[32:33], v[32:33], 1.0 op_sel_hi:[1,0]
	v_pk_add_f32 v[28:29], v[28:29], 1.0 op_sel_hi:[1,0]
	v_rcp_f32_e32 v30, v30
	v_rcp_f32_e32 v26, v26
	v_rcp_f32_e32 v31, v31
	v_rcp_f32_e32 v27, v27
	v_rcp_f32_e32 v32, v32
	v_rcp_f32_e32 v28, v28
	v_rcp_f32_e32 v33, v33
	v_rcp_f32_e32 v29, v29
.LBB0_1138:
	v_mov_b32_e32 v93, v92
	v_cvt_pk_bf16_f32 v30, v30, v31
	v_cvt_pk_bf16_f32 v31, v32, v33
	v_cvt_pk_bf16_f32 v32, v26, v27
	v_mov_b32_e32 v26, v92
	v_mov_b32_e32 v27, v92
	v_pk_mul_f32 v[24:25], v[24:25], v[26:27]
	v_pk_mul_f32 v[22:23], v[22:23], v[92:93]
	v_pk_mul_f32 v[20:21], v[20:21], v[26:27]
	s_and_b64 vcc, exec, s[0:1]
	v_pk_mul_f32 v[18:19], v[18:19], v[92:93]
	v_cvt_pk_bf16_f32 v33, v28, v29
	global_store_dwordx4 v[90:91], v[30:33], off offset:256
	s_cbranch_vccnz .LBB0_1140
	v_pk_add_f32 v[22:23], v[22:23], v[134:135]
	v_pk_add_f32 v[18:19], v[18:19], v[130:131]
	v_pk_add_f32 v[24:25], v[24:25], v[136:137]
	v_pk_add_f32 v[20:21], v[20:21], v[132:133]
	v_pk_mul_f32 v[22:23], v[22:23], v[178:179]
	v_pk_mul_f32 v[18:19], v[18:19], v[178:179]
	v_pk_mul_f32 v[24:25], v[24:25], v[178:179]
	v_pk_mul_f32 v[20:21], v[20:21], v[178:179]
	v_exp_f32_e32 v22, v22
	v_exp_f32_e32 v18, v18
	v_exp_f32_e32 v23, v23
	v_exp_f32_e32 v19, v19
	v_exp_f32_e32 v24, v24
	v_exp_f32_e32 v20, v20
	v_exp_f32_e32 v25, v25
	v_exp_f32_e32 v21, v21
	v_pk_add_f32 v[22:23], v[22:23], 1.0 op_sel_hi:[1,0]
	v_pk_add_f32 v[18:19], v[18:19], 1.0 op_sel_hi:[1,0]
	v_pk_add_f32 v[24:25], v[24:25], 1.0 op_sel_hi:[1,0]
	v_pk_add_f32 v[20:21], v[20:21], 1.0 op_sel_hi:[1,0]
	v_rcp_f32_e32 v22, v22
	v_rcp_f32_e32 v18, v18
	v_rcp_f32_e32 v23, v23
	v_rcp_f32_e32 v19, v19
	v_rcp_f32_e32 v24, v24
	v_rcp_f32_e32 v20, v20
	v_rcp_f32_e32 v25, v25
	v_rcp_f32_e32 v21, v21
.LBB0_1140:
	v_mov_b32_e32 v85, v84
	v_cvt_pk_bf16_f32 v22, v22, v23
	v_cvt_pk_bf16_f32 v23, v24, v25
	v_cvt_pk_bf16_f32 v24, v18, v19
	v_mov_b32_e32 v18, v84
	v_mov_b32_e32 v19, v84
	v_pk_mul_f32 v[16:17], v[16:17], v[18:19]
	v_pk_mul_f32 v[14:15], v[14:15], v[84:85]
	v_pk_mul_f32 v[12:13], v[12:13], v[18:19]
	s_and_b64 vcc, exec, s[0:1]
	v_pk_mul_f32 v[10:11], v[10:11], v[84:85]
	v_cvt_pk_bf16_f32 v25, v20, v21
	global_store_dwordx4 v[82:83], v[22:25], off offset:256
	s_cbranch_vccnz .LBB0_1142
	v_pk_add_f32 v[14:15], v[14:15], v[134:135]
	v_pk_add_f32 v[10:11], v[10:11], v[130:131]
	v_pk_add_f32 v[16:17], v[16:17], v[136:137]
	v_pk_add_f32 v[12:13], v[12:13], v[132:133]
	v_pk_mul_f32 v[14:15], v[14:15], v[178:179]
	v_pk_mul_f32 v[10:11], v[10:11], v[178:179]
	v_pk_mul_f32 v[16:17], v[16:17], v[178:179]
	v_pk_mul_f32 v[12:13], v[12:13], v[178:179]
	v_exp_f32_e32 v14, v14
	v_exp_f32_e32 v10, v10
	v_exp_f32_e32 v15, v15
	v_exp_f32_e32 v11, v11
	v_exp_f32_e32 v16, v16
	v_exp_f32_e32 v12, v12
	v_exp_f32_e32 v17, v17
	v_exp_f32_e32 v13, v13
	v_pk_add_f32 v[14:15], v[14:15], 1.0 op_sel_hi:[1,0]
	v_pk_add_f32 v[10:11], v[10:11], 1.0 op_sel_hi:[1,0]
	v_pk_add_f32 v[16:17], v[16:17], 1.0 op_sel_hi:[1,0]
	v_pk_add_f32 v[12:13], v[12:13], 1.0 op_sel_hi:[1,0]
	v_rcp_f32_e32 v14, v14
	v_rcp_f32_e32 v10, v10
	v_rcp_f32_e32 v15, v15
	v_rcp_f32_e32 v11, v11
	v_rcp_f32_e32 v16, v16
	v_rcp_f32_e32 v12, v12
	v_rcp_f32_e32 v17, v17
	v_rcp_f32_e32 v13, v13
.LBB0_1142:
	v_mov_b32_e32 v77, v76
	v_cvt_pk_bf16_f32 v14, v14, v15
	v_cvt_pk_bf16_f32 v15, v16, v17
	v_cvt_pk_bf16_f32 v16, v10, v11
	v_mov_b32_e32 v10, v76
	v_mov_b32_e32 v11, v76
	v_pk_mul_f32 v[8:9], v[8:9], v[10:11]
	v_pk_mul_f32 v[6:7], v[6:7], v[76:77]
	v_pk_mul_f32 v[4:5], v[4:5], v[10:11]
	s_and_b64 vcc, exec, s[0:1]
	v_pk_mul_f32 v[2:3], v[2:3], v[76:77]
	v_cvt_pk_bf16_f32 v17, v12, v13
	global_store_dwordx4 v[74:75], v[14:17], off offset:256
	s_cbranch_vccnz .LBB0_1032
	v_pk_add_f32 v[6:7], v[6:7], v[134:135]
	v_pk_add_f32 v[2:3], v[2:3], v[130:131]
	v_pk_add_f32 v[8:9], v[8:9], v[136:137]
	v_pk_add_f32 v[4:5], v[4:5], v[132:133]
	v_pk_mul_f32 v[6:7], v[6:7], v[178:179]
	v_pk_mul_f32 v[2:3], v[2:3], v[178:179]
	v_pk_mul_f32 v[8:9], v[8:9], v[178:179]
	v_pk_mul_f32 v[4:5], v[4:5], v[178:179]
	v_exp_f32_e32 v6, v6
	v_exp_f32_e32 v2, v2
	v_exp_f32_e32 v7, v7
	v_exp_f32_e32 v3, v3
	v_exp_f32_e32 v8, v8
	v_exp_f32_e32 v4, v4
	v_exp_f32_e32 v9, v9
	v_exp_f32_e32 v5, v5
	v_pk_add_f32 v[6:7], v[6:7], 1.0 op_sel_hi:[1,0]
	v_pk_add_f32 v[2:3], v[2:3], 1.0 op_sel_hi:[1,0]
	v_pk_add_f32 v[8:9], v[8:9], 1.0 op_sel_hi:[1,0]
	v_pk_add_f32 v[4:5], v[4:5], 1.0 op_sel_hi:[1,0]
	v_rcp_f32_e32 v6, v6
	v_rcp_f32_e32 v2, v2
	v_rcp_f32_e32 v7, v7
	v_rcp_f32_e32 v3, v3
	v_rcp_f32_e32 v8, v8
	v_rcp_f32_e32 v4, v4
	v_rcp_f32_e32 v9, v9
	v_rcp_f32_e32 v5, v5
	s_branch .LBB0_1032
